# attention: the later-dispatched half of the grid (workgroup id bit 8, measured ~6% slower per tile) keeps priority 1 between its MFMA sections instead of dropping to 0, balancing the two co-resident w
# speedup vs baseline: 1.0145x; 1.0145x over previous
.Lattn_ld:
	global_load_dwordx4 v[164:167], v[190:191], off
	global_load_dwordx4 v[148:151], v[190:191], off offset:64
	global_load_dwordx4 v[152:155], v[190:191], off offset:128
	global_load_dwordx4 v[172:175], v[190:191], off offset:192
	global_load_dwordx4 v[156:159], v[242:243], off
	global_load_dwordx4 v[160:163], v[242:243], off offset:64
	v_add_co_u32_e32 v190, vcc, s79, v252
	s_nop 1
	v_addc_co_u32_e32 v191, vcc, 0, v253, vcc
	global_load_dwordx4 v[144:147], v[252:253], off
	global_load_dwordx4 v[168:171], v[190:191], off
	v_add_co_u32_e32 v190, vcc, 0x100000, v252
	s_nop 1
	v_addc_co_u32_e32 v191, vcc, 0, v253, vcc
	v_add_co_u32_e32 v242, vcc, 0x180000, v252
	s_nop 1
	v_addc_co_u32_e32 v243, vcc, 0, v253, vcc
	global_load_dwordx4 v[176:179], v[190:191], off
	global_load_dwordx4 v[180:183], v[242:243], off
	s_cmp_le_i32 s15, s17
	s_cbranch_scc0 .LBB0_57
	s_setprio 1
	s_waitcnt lgkmcnt(7)
	v_mfma_f32_32x32x16_bf16 v[80:95], v[244:247], v[96:99], 0
	ds_read_b128 v[244:247], v220 offset:256
	s_waitcnt lgkmcnt(7)
	v_mfma_f32_32x32x16_bf16 v[80:95], v[248:251], v[100:103], v[80:95]
	ds_read_b128 v[248:251], v220 offset:288
	s_waitcnt lgkmcnt(7)
	v_mfma_f32_32x32x16_bf16 v[80:95], v[222:225], v[104:107], v[80:95]
	ds_read_b128 v[222:225], v220 offset:320
	s_waitcnt lgkmcnt(7)
	v_mfma_f32_32x32x16_bf16 v[80:95], v[230:233], v[108:111], v[80:95]
	ds_read_b128 v[230:233], v220 offset:352
	s_waitcnt lgkmcnt(7)
	v_mfma_f32_32x32x16_bf16 v[80:95], v[64:67], v[112:115], v[80:95]
	s_waitcnt lgkmcnt(6)
	v_mfma_f32_32x32x16_bf16 v[80:95], v[68:71], v[116:119], v[80:95]
	s_waitcnt lgkmcnt(5)
	v_mfma_f32_32x32x16_bf16 v[80:95], v[72:75], v[120:123], v[80:95]
	s_waitcnt lgkmcnt(4)
	v_mfma_f32_32x32x16_bf16 v[80:95], v[76:79], v[124:127], v[80:95]
	s_waitcnt lgkmcnt(3)
	v_mfma_f32_32x32x16_bf16 v[80:95], v[244:247], v[128:131], v[80:95]
	ds_read_b128 v[244:247], v220 offset:12800
	s_waitcnt lgkmcnt(3)
	v_mfma_f32_32x32x16_bf16 v[80:95], v[248:251], v[132:135], v[80:95]
	ds_read_b128 v[248:251], v220 offset:12832
	s_waitcnt lgkmcnt(3)
	v_mfma_f32_32x32x16_bf16 v[80:95], v[222:225], v[136:139], v[80:95]
	ds_read_b128 v[222:225], v220 offset:12864
	s_waitcnt lgkmcnt(3)
	v_mfma_f32_32x32x16_bf16 v[80:95], v[230:233], v[140:143], v[80:95]
	ds_read_b128 v[230:233], v220 offset:12896
	s_waitcnt lgkmcnt(3)
	v_mfma_f32_32x32x16_bf16 v[64:79], v[244:247], v[96:99], 0
	ds_read_b128 v[244:247], v220 offset:12928
	s_waitcnt lgkmcnt(3)
	v_mfma_f32_32x32x16_bf16 v[64:79], v[248:251], v[100:103], v[64:79]
	ds_read_b128 v[248:251], v220 offset:12960
	s_waitcnt lgkmcnt(3)
	v_mfma_f32_32x32x16_bf16 v[64:79], v[222:225], v[104:107], v[64:79]
	ds_read_b128 v[222:225], v220 offset:12992
	s_waitcnt lgkmcnt(3)
	v_mfma_f32_32x32x16_bf16 v[64:79], v[230:233], v[108:111], v[64:79]
	ds_read_b128 v[230:233], v220 offset:13024
	s_waitcnt lgkmcnt(3)
	v_mfma_f32_32x32x16_bf16 v[64:79], v[244:247], v[112:115], v[64:79]
	ds_read_b128 v[244:247], v220 offset:13056
	s_waitcnt lgkmcnt(3)
	v_mfma_f32_32x32x16_bf16 v[64:79], v[248:251], v[116:119], v[64:79]
	ds_read_b128 v[248:251], v220 offset:13088
	s_waitcnt lgkmcnt(3)
	v_mfma_f32_32x32x16_bf16 v[64:79], v[222:225], v[120:123], v[64:79]
	ds_read_b128 v[222:225], v220 offset:13120
	s_waitcnt lgkmcnt(3)
	v_mfma_f32_32x32x16_bf16 v[64:79], v[230:233], v[124:127], v[64:79]
	ds_read_b128 v[230:233], v220 offset:13152
	s_waitcnt lgkmcnt(3)
	v_mfma_f32_32x32x16_bf16 v[64:79], v[244:247], v[128:131], v[64:79]
	s_waitcnt lgkmcnt(2)
	v_mfma_f32_32x32x16_bf16 v[64:79], v[248:251], v[132:135], v[64:79]
	s_waitcnt lgkmcnt(1)
	v_mfma_f32_32x32x16_bf16 v[64:79], v[222:225], v[136:139], v[64:79]
	s_waitcnt lgkmcnt(0)
	v_mfma_f32_32x32x16_bf16 v[64:79], v[230:233], v[140:143], v[64:79]
	s_bitcmp1_b32 s50, 8
	s_cbranch_scc1 .Lprio_keep0
	s_setprio 0
.Lprio_keep0:
	ds_read_b128 v[244:247], v239 offset:25600
	ds_read_b128 v[248:251], v239 offset:30208
	ds_read_b128 v[222:225], v239 offset:34816
	ds_read_b128 v[230:233], v239 offset:39424
	s_add_i32 s4, s15, 63
	s_cmp_gt_i32 s4, s18
	s_cbranch_scc0 .Lattn_nomask
	v_add_u32_e32 v220, s15, v197
	v_cmp_gt_i32_e32 vcc, v220, v214
	s_nop 1
	v_cndmask_b32_e32 v221, v80, v234, vcc
	v_cmp_lt_i32_e32 vcc, v220, v214
	s_nop 1
	v_cndmask_b32_e32 v80, v221, v80, vcc
	v_add_u32_e32 v221, 2, v220
	v_cndmask_b32_e32 v81, v234, v81, vcc
	v_cmp_le_i32_e32 vcc, v221, v214
	v_add_u32_e32 v221, 3, v220
	s_nop 0
	v_cndmask_b32_e32 v82, v234, v82, vcc
	v_cmp_le_i32_e32 vcc, v221, v214
	v_add_u32_e32 v221, 8, v220
	s_nop 0
	v_cndmask_b32_e32 v83, v234, v83, vcc
	v_cmp_le_i32_e32 vcc, v221, v214
	v_add_u32_e32 v221, 9, v220
	s_nop 0
	v_cndmask_b32_e32 v84, v234, v84, vcc
	v_cmp_le_i32_e32 vcc, v221, v214
	v_add_u32_e32 v221, 10, v220
	s_nop 0
	v_cndmask_b32_e32 v85, v234, v85, vcc
	v_cmp_le_i32_e32 vcc, v221, v214
	v_add_u32_e32 v221, 11, v220
	s_nop 0
	v_cndmask_b32_e32 v86, v234, v86, vcc
	v_cmp_le_i32_e32 vcc, v221, v214
	v_add_u32_e32 v221, 16, v220
	s_nop 0
	v_cndmask_b32_e32 v87, v234, v87, vcc
	v_cmp_le_i32_e32 vcc, v221, v214
	v_add_u32_e32 v221, 17, v220
	s_nop 0
	v_cndmask_b32_e32 v88, v234, v88, vcc
	v_cmp_le_i32_e32 vcc, v221, v214
	v_add_u32_e32 v221, 18, v220
	s_nop 0
	v_cndmask_b32_e32 v89, v234, v89, vcc
	v_cmp_le_i32_e32 vcc, v221, v214
	v_add_u32_e32 v221, 19, v220
	s_nop 0
	v_cndmask_b32_e32 v90, v234, v90, vcc
	v_cmp_le_i32_e32 vcc, v221, v214
	v_add_u32_e32 v221, 24, v220
	s_nop 0
	v_cndmask_b32_e32 v91, v234, v91, vcc
	v_cmp_le_i32_e32 vcc, v221, v214
	v_add_u32_e32 v221, 25, v220
	s_nop 0
	v_cndmask_b32_e32 v92, v234, v92, vcc
	v_cmp_le_i32_e32 vcc, v221, v214
	v_add_u32_e32 v221, 26, v220
	s_nop 0
	v_cndmask_b32_e32 v93, v234, v93, vcc
	v_cmp_le_i32_e32 vcc, v221, v214
	v_add_u32_e32 v221, 27, v220
	s_nop 0
	v_cndmask_b32_e32 v94, v234, v94, vcc
	v_cmp_le_i32_e32 vcc, v221, v214
	v_add_u32_e32 v221, 32, v220
	s_nop 0
	v_cndmask_b32_e32 v95, v234, v95, vcc
	v_cmp_le_i32_e32 vcc, v221, v214
	v_add_u32_e32 v221, 33, v220
	s_nop 0
	v_cndmask_b32_e32 v64, v234, v64, vcc
	v_cmp_le_i32_e32 vcc, v221, v214
	v_add_u32_e32 v221, 34, v220
	s_nop 0
	v_cndmask_b32_e32 v65, v234, v65, vcc
	v_cmp_le_i32_e32 vcc, v221, v214
	v_add_u32_e32 v221, 35, v220
	s_nop 0
	v_cndmask_b32_e32 v66, v234, v66, vcc
	v_cmp_le_i32_e32 vcc, v221, v214
	v_add_u32_e32 v221, 40, v220
	s_nop 0
	v_cndmask_b32_e32 v67, v234, v67, vcc
	v_cmp_le_i32_e32 vcc, v221, v214
	v_add_u32_e32 v221, 41, v220
	s_nop 0
	v_cndmask_b32_e32 v68, v234, v68, vcc
	v_cmp_le_i32_e32 vcc, v221, v214
	v_add_u32_e32 v221, 42, v220
	s_nop 0
	v_cndmask_b32_e32 v69, v234, v69, vcc
	v_cmp_le_i32_e32 vcc, v221, v214
	v_add_u32_e32 v221, 43, v220
	s_nop 0
	v_cndmask_b32_e32 v70, v234, v70, vcc
	v_cmp_le_i32_e32 vcc, v221, v214
	v_add_u32_e32 v221, 48, v220
	s_nop 0
	v_cndmask_b32_e32 v71, v234, v71, vcc
	v_cmp_le_i32_e32 vcc, v221, v214
	v_add_u32_e32 v221, 49, v220
	s_nop 0
	v_cndmask_b32_e32 v72, v234, v72, vcc
	v_cmp_le_i32_e32 vcc, v221, v214
	v_add_u32_e32 v221, 50, v220
	s_nop 0
	v_cndmask_b32_e32 v73, v234, v73, vcc
	v_cmp_le_i32_e32 vcc, v221, v214
	v_add_u32_e32 v221, 51, v220
	s_nop 0
	v_cndmask_b32_e32 v74, v234, v74, vcc
	v_cmp_le_i32_e32 vcc, v221, v214
	v_add_u32_e32 v221, 56, v220
	s_nop 0
	v_cndmask_b32_e32 v75, v234, v75, vcc
	v_cmp_le_i32_e32 vcc, v221, v214
	v_add_u32_e32 v221, 57, v220
	s_nop 0
	v_cndmask_b32_e32 v76, v234, v76, vcc
	v_cmp_le_i32_e32 vcc, v221, v214
	v_add_u32_e32 v221, 58, v220
	v_add_u32_e32 v220, 59, v220
	v_cndmask_b32_e32 v77, v234, v77, vcc
	v_cmp_le_i32_e32 vcc, v221, v214
	s_nop 1
	v_cndmask_b32_e32 v78, v234, v78, vcc
	v_cmp_le_i32_e32 vcc, v220, v214
	s_nop 1
	v_cndmask_b32_e32 v79, v234, v79, vcc

.Lattn_noresc:
	v_sub_f32_e32 v80, v80, v241
	v_sub_f32_e32 v81, v81, v241
	v_sub_f32_e32 v82, v82, v241
	v_sub_f32_e32 v83, v83, v241
	v_sub_f32_e32 v84, v84, v241
	v_sub_f32_e32 v85, v85, v241
	v_sub_f32_e32 v86, v86, v241
	v_sub_f32_e32 v87, v87, v241
	v_sub_f32_e32 v88, v88, v241
	v_sub_f32_e32 v89, v89, v241
	v_sub_f32_e32 v90, v90, v241
	v_sub_f32_e32 v91, v91, v241
	v_sub_f32_e32 v92, v92, v241
	v_sub_f32_e32 v93, v93, v241
	v_sub_f32_e32 v94, v94, v241
	v_sub_f32_e32 v95, v95, v241
	v_sub_f32_e32 v64, v64, v241
	v_sub_f32_e32 v65, v65, v241
	v_sub_f32_e32 v66, v66, v241
	v_sub_f32_e32 v67, v67, v241
	v_sub_f32_e32 v68, v68, v241
	v_sub_f32_e32 v69, v69, v241
	v_sub_f32_e32 v70, v70, v241
	v_sub_f32_e32 v71, v71, v241
	v_sub_f32_e32 v72, v72, v241
	v_sub_f32_e32 v73, v73, v241
	v_sub_f32_e32 v74, v74, v241
	v_sub_f32_e32 v75, v75, v241
	v_sub_f32_e32 v76, v76, v241
	v_sub_f32_e32 v77, v77, v241
	v_sub_f32_e32 v78, v78, v241
	v_sub_f32_e32 v79, v79, v241
	v_exp_f32_e32 v80, v80
	v_exp_f32_e32 v81, v81
	v_exp_f32_e32 v82, v82
	v_add_f32_e32 v221, v80, v81
	v_exp_f32_e32 v83, v83
	v_add_f32_e32 v221, v221, v82
	v_exp_f32_e32 v84, v84
	v_add_f32_e32 v221, v221, v83
	v_exp_f32_e32 v85, v85
	v_add_f32_e32 v221, v221, v84
	v_exp_f32_e32 v86, v86
	v_add_f32_e32 v221, v221, v85
	v_exp_f32_e32 v87, v87
	v_add_f32_e32 v221, v221, v86
	v_exp_f32_e32 v88, v88
	v_add_f32_e32 v221, v221, v87
	v_exp_f32_e32 v89, v89
	v_add_f32_e32 v221, v221, v88
	v_exp_f32_e32 v90, v90
	v_add_f32_e32 v221, v221, v89
	v_exp_f32_e32 v91, v91
	v_add_f32_e32 v221, v221, v90
	v_exp_f32_e32 v92, v92
	v_add_f32_e32 v221, v221, v91
	v_exp_f32_e32 v93, v93
	v_add_f32_e32 v221, v221, v92
	v_exp_f32_e32 v94, v94
	v_add_f32_e32 v221, v221, v93
	v_exp_f32_e32 v95, v95
	v_add_f32_e32 v221, v221, v94
	v_exp_f32_e32 v64, v64
	v_add_f32_e32 v221, v221, v95
	v_exp_f32_e32 v65, v65
	v_add_f32_e32 v221, v221, v64
	v_exp_f32_e32 v66, v66
	v_add_f32_e32 v221, v221, v65
	v_exp_f32_e32 v67, v67
	v_add_f32_e32 v221, v221, v66
	v_exp_f32_e32 v68, v68
	v_add_f32_e32 v221, v221, v67
	v_exp_f32_e32 v69, v69
	v_add_f32_e32 v221, v221, v68
	v_exp_f32_e32 v70, v70
	v_add_f32_e32 v221, v221, v69
	v_exp_f32_e32 v71, v71
	v_add_f32_e32 v221, v221, v70
	v_exp_f32_e32 v72, v72
	v_add_f32_e32 v221, v221, v71
	v_exp_f32_e32 v73, v73
	v_add_f32_e32 v221, v221, v72
	v_exp_f32_e32 v74, v74
	v_add_f32_e32 v221, v221, v73
	v_exp_f32_e32 v75, v75
	v_add_f32_e32 v221, v221, v74
	v_exp_f32_e32 v76, v76
	v_add_f32_e32 v221, v221, v75
	v_exp_f32_e32 v77, v77
	v_add_f32_e32 v221, v221, v76
	v_exp_f32_e32 v78, v78
	v_add_f32_e32 v221, v221, v77
	v_exp_f32_e32 v79, v79
	v_add_f32_e32 v221, v221, v78
	s_nop 0
	v_add_f32_e32 v221, v221, v79
	v_fmac_f32_e32 v221, v215, v220
	v_cvt_pk_bf16_f32 v80, v80, v81
	v_cvt_pk_bf16_f32 v81, v82, v83
	v_cvt_pk_bf16_f32 v82, v84, v85
	v_cvt_pk_bf16_f32 v83, v86, v87
	v_cvt_pk_bf16_f32 v88, v88, v89
	v_cvt_pk_bf16_f32 v89, v90, v91
	v_cvt_pk_bf16_f32 v90, v92, v93
	v_cvt_pk_bf16_f32 v91, v94, v95
	v_cvt_pk_bf16_f32 v64, v64, v65
	v_cvt_pk_bf16_f32 v65, v66, v67
	v_cvt_pk_bf16_f32 v66, v68, v69
	v_cvt_pk_bf16_f32 v67, v70, v71
	v_cvt_pk_bf16_f32 v72, v72, v73
	v_cvt_pk_bf16_f32 v73, v74, v75
	v_cvt_pk_bf16_f32 v74, v76, v77
	v_cvt_pk_bf16_f32 v75, v78, v79
	v_mov_b32_e32 v215, v221
	v_mov_b32_e32 v240, v241
	ds_read_b128 v[84:87], v239 offset:25632
	ds_read_b128 v[92:95], v239 offset:30240
	ds_read_b128 v[68:71], v239 offset:34848
	ds_read_b128 v[76:79], v239 offset:39456
	s_setprio 1
	s_waitcnt lgkmcnt(7)
	v_mfma_f32_32x32x16_bf16 v[48:63], v[244:247], v[80:83], v[48:63]
	ds_read_b128 v[244:247], v239 offset:25664
	s_waitcnt lgkmcnt(7)
	v_mfma_f32_32x32x16_bf16 v[32:47], v[248:251], v[80:83], v[32:47]
	ds_read_b128 v[248:251], v239 offset:30272
	s_waitcnt lgkmcnt(7)
	v_mfma_f32_32x32x16_bf16 v[16:31], v[222:225], v[80:83], v[16:31]
	ds_read_b128 v[222:225], v239 offset:34880
	s_waitcnt lgkmcnt(7)
	v_mfma_f32_32x32x16_bf16 v[0:15], v[230:233], v[80:83], v[0:15]
	ds_read_b128 v[230:233], v239 offset:39488
	s_waitcnt lgkmcnt(7)
	v_mfma_f32_32x32x16_bf16 v[48:63], v[84:87], v[88:91], v[48:63]
	ds_read_b128 v[84:87], v239 offset:25696
	s_waitcnt lgkmcnt(7)
	v_mfma_f32_32x32x16_bf16 v[32:47], v[92:95], v[88:91], v[32:47]
	ds_read_b128 v[92:95], v239 offset:30304
	s_waitcnt lgkmcnt(7)
	v_mfma_f32_32x32x16_bf16 v[16:31], v[68:71], v[88:91], v[16:31]
	ds_read_b128 v[68:71], v239 offset:34912
	s_waitcnt lgkmcnt(7)
	v_mfma_f32_32x32x16_bf16 v[0:15], v[76:79], v[88:91], v[0:15]
	ds_read_b128 v[76:79], v239 offset:39520
	s_waitcnt lgkmcnt(7)
	v_mfma_f32_32x32x16_bf16 v[48:63], v[244:247], v[64:67], v[48:63]
	s_waitcnt lgkmcnt(6)
	v_mfma_f32_32x32x16_bf16 v[32:47], v[248:251], v[64:67], v[32:47]
	s_waitcnt lgkmcnt(5)
	v_mfma_f32_32x32x16_bf16 v[16:31], v[222:225], v[64:67], v[16:31]
	s_waitcnt lgkmcnt(4)
	v_mfma_f32_32x32x16_bf16 v[0:15], v[230:233], v[64:67], v[0:15]
	s_waitcnt lgkmcnt(3)
	v_mfma_f32_32x32x16_bf16 v[48:63], v[84:87], v[72:75], v[48:63]
	s_waitcnt lgkmcnt(2)
	v_mfma_f32_32x32x16_bf16 v[32:47], v[92:95], v[72:75], v[32:47]
	s_waitcnt lgkmcnt(1)
	v_mfma_f32_32x32x16_bf16 v[16:31], v[68:71], v[72:75], v[16:31]
	s_waitcnt lgkmcnt(0)
	v_mfma_f32_32x32x16_bf16 v[0:15], v[76:79], v[72:75], v[0:15]
	s_bitcmp1_b32 s50, 8
	s_cbranch_scc1 .Lprio_keep1
	s_setprio 0
.Lprio_keep1:
.LBB0_57:
	s_add_i32 s13, s13, 1
	s_cmp_eq_u32 s12, s13
	s_cbranch_scc1 .LBB0_43
	s_mov_b32 s15, s14
	s_branch .LBB0_51
.LBB0_59:
	s_setprio 0
	v_mov_b32_e32 v188, 0x358637bd
	v_mov_b64_e32 v[190:191], 0x3d81000
	v_mov_b32_e32 v222, 0x1000
	v_mov_b32_e32 v223, 0x2000
	v_mov_b32_e32 v224, 0xff03000
	v_mov_b32_e32 v225, 1
	v_xor_b32_e32 v230, 8, v226
	v_xor_b32_e32 v231, 4, v226
	v_xor_b32_e32 v232, 2, v226
	v_xor_b32_e32 v233, 1, v226
	v_mov_b32_e32 v242, v187
	v_mov_b32_e32 v243, v187
	s_mov_b64 s[0:1], 0
